# ret_state: decay VALU runs under the fragment reads; each of the four MFMAs waits only for its own fragments (counted lgkmcnt)
# speedup vs baseline: 1.0036x; 1.0036x over previous
.LBB0_1876:
	s_cmp_eq_u32 s21, 32
	s_cbranch_scc1 .LBB0_1891
	ds_read_b64_tr_b16 v[88:89], v1 offset:0
	ds_read_b64_tr_b16 v[90:91], v1 offset:0x800
	ds_read_b64_tr_b16 v[92:93], v69 offset:0
	ds_read_b64_tr_b16 v[94:95], v69 offset:0x800
	ds_read_b64_tr_b16 v[96:97], v1 offset:0x1000
	ds_read_b64_tr_b16 v[98:99], v1 offset:0x1800
	ds_read_b64_tr_b16 v[100:101], v69 offset:0x1000
	ds_read_b64_tr_b16 v[102:103], v69 offset:0x1800
	ds_read_b64_tr_b16 v[104:105], v1 offset:0x2000
	ds_read_b64_tr_b16 v[106:107], v1 offset:0x2800
	ds_read_b64_tr_b16 v[108:109], v69 offset:0x2000
	ds_read_b64_tr_b16 v[110:111], v69 offset:0x2800
	ds_read_b64_tr_b16 v[112:113], v1 offset:0x3000
	ds_read_b64_tr_b16 v[114:115], v1 offset:0x3800
	ds_read_b64_tr_b16 v[116:117], v69 offset:0x3000
	ds_read_b64_tr_b16 v[118:119], v69 offset:0x3800
	v_mov_b32_e32 v77, v76
	s_xor_b64 s[14:15], s[14:15], -1
	v_pk_mul_f32 v[16:17], v[76:77], v[16:17]
	v_pk_mul_f32 v[14:15], v[76:77], v[14:15]
	v_pk_mul_f32 v[12:13], v[76:77], v[12:13]
	v_pk_mul_f32 v[10:11], v[76:77], v[10:11]
	v_pk_mul_f32 v[8:9], v[76:77], v[8:9]
	v_pk_mul_f32 v[6:7], v[76:77], v[6:7]
	v_pk_mul_f32 v[4:5], v[76:77], v[4:5]
	v_pk_mul_f32 v[2:3], v[80:81], v[2:3]
	v_pk_mul_f32 v[32:33], v[76:77], v[32:33]
	v_pk_mul_f32 v[30:31], v[76:77], v[30:31]
	v_pk_mul_f32 v[28:29], v[76:77], v[28:29]
	v_pk_mul_f32 v[26:27], v[76:77], v[26:27]
	v_pk_mul_f32 v[24:25], v[76:77], v[24:25]
	v_pk_mul_f32 v[22:23], v[76:77], v[22:23]
	v_pk_mul_f32 v[20:21], v[76:77], v[20:21]
	v_pk_mul_f32 v[18:19], v[80:81], v[18:19]
	s_waitcnt lgkmcnt(12)
	v_mfma_f32_32x32x16_bf16 v[2:17], v[88:91], v[92:95], v[2:17]
	s_mov_b64 s[16:17], -1
	s_cmp_lt_u32 s21, 34
	s_waitcnt lgkmcnt(8)
	v_mfma_f32_32x32x16_bf16 v[18:33], v[96:99], v[100:103], v[18:33]
	s_waitcnt lgkmcnt(4)
	v_mfma_f32_32x32x16_bf16 v[2:17], v[104:107], v[108:111], v[2:17]
	s_waitcnt lgkmcnt(0)
	v_mfma_f32_32x32x16_bf16 v[18:33], v[112:115], v[116:119], v[18:33]
	s_cbranch_scc0 .LBB0_1882
	s_and_b64 vcc, exec, s[14:15]
	s_cbranch_vccz .LBB0_1879
	s_waitcnt vmcnt(4)
	s_mov_b64 s[16:17], 0

.LBB0_1886:
	ds_read_b64_tr_b16 v[86:87], v84 offset:0
	ds_read_b64_tr_b16 v[88:89], v84 offset:0x800
	ds_read_b64_tr_b16 v[90:91], v85 offset:0
	ds_read_b64_tr_b16 v[92:93], v85 offset:0x800
	ds_read_b64_tr_b16 v[94:95], v84 offset:0x1000
	ds_read_b64_tr_b16 v[96:97], v84 offset:0x1800
	ds_read_b64_tr_b16 v[98:99], v85 offset:0x1000
	ds_read_b64_tr_b16 v[100:101], v85 offset:0x1800
	ds_read_b64_tr_b16 v[102:103], v84 offset:0x2000
	ds_read_b64_tr_b16 v[104:105], v84 offset:0x2800
	ds_read_b64_tr_b16 v[106:107], v85 offset:0x2000
	ds_read_b64_tr_b16 v[108:109], v85 offset:0x2800
	ds_read_b64_tr_b16 v[110:111], v84 offset:0x3000
	ds_read_b64_tr_b16 v[112:113], v84 offset:0x3800
	ds_read_b64_tr_b16 v[114:115], v85 offset:0x3000
	ds_read_b64_tr_b16 v[116:117], v85 offset:0x3800
	v_mov_b32_e32 v77, v76
	v_pk_mul_f32 v[16:17], v[76:77], v[16:17]
	v_pk_mul_f32 v[14:15], v[76:77], v[14:15]
	v_pk_mul_f32 v[12:13], v[76:77], v[12:13]
	v_pk_mul_f32 v[10:11], v[76:77], v[10:11]
	v_pk_mul_f32 v[8:9], v[76:77], v[8:9]
	v_pk_mul_f32 v[6:7], v[76:77], v[6:7]
	v_pk_mul_f32 v[4:5], v[76:77], v[4:5]
	v_pk_mul_f32 v[2:3], v[80:81], v[2:3]
	v_pk_mul_f32 v[32:33], v[76:77], v[32:33]
	v_pk_mul_f32 v[30:31], v[76:77], v[30:31]
	v_pk_mul_f32 v[28:29], v[76:77], v[28:29]
	v_pk_mul_f32 v[26:27], v[76:77], v[26:27]
	v_pk_mul_f32 v[24:25], v[76:77], v[24:25]
	v_pk_mul_f32 v[22:23], v[76:77], v[22:23]
	v_pk_mul_f32 v[20:21], v[76:77], v[20:21]
	v_pk_mul_f32 v[18:19], v[80:81], v[18:19]
	s_waitcnt lgkmcnt(12)
	v_mfma_f32_32x32x16_bf16 v[2:17], v[86:89], v[90:93], v[2:17]
	s_andn2_b64 vcc, exec, s[12:13]
	s_waitcnt lgkmcnt(8)
	v_mfma_f32_32x32x16_bf16 v[18:33], v[94:97], v[98:101], v[18:33]
	s_waitcnt lgkmcnt(4)
	v_mfma_f32_32x32x16_bf16 v[2:17], v[102:105], v[106:109], v[2:17]
	s_waitcnt lgkmcnt(0)
	v_mfma_f32_32x32x16_bf16 v[18:33], v[110:113], v[114:117], v[18:33]
	s_cbranch_vccnz .LBB0_1869
	s_mov_b64 s[12:13], -1
	s_and_b64 vcc, exec, s[14:15]
	s_cbranch_vccz .LBB0_1889
	s_waitcnt vmcnt(4)
	s_mov_b64 s[12:13], 0
